# P5 idle-tail table conversion limited to 1 unit per workgroup (rest converted in P7's idle tail)
# speedup vs baseline: 1.0140x; 1.0003x over previous
; __device__ __forceinline__ int lane_id_v() { int l; asm volatile("v_mbcnt_lo_u32_b32 %0, -1, 0\n\tv_mbcnt_hi_u32_b32 %0, -1, %0" : "=v"(l)); return l; }
; __device__ __forceinline__ void cvt_tables_drain(Frame& F, int max_units) {
;     volatile unsigned* slot = (volatile unsigned*)(F.lds + MISC_OFF + 64);
;     for (int n = 0; n < max_units; ++n) {
;         __syncthreads();
;         if ((F.wave * 64 + lane_id_v()) == 0) *slot = __hip_atomic_fetch_add((unsigned*)(F.ctl + CW_QUEUE + 64 * 8), 1u, __ATOMIC_RELAXED, __HIP_MEMORY_SCOPE_AGENT);
;         __syncthreads();
;         const int u = __builtin_amdgcn_readfirstlane((int)*slot);
;         if (u >= 512) break;
;         cvt_tables_unit(F, u);
;     }
; }
; __global__ void __launch_bounds__(NWAVES * 64, 2) fwd_kernel(Args args) {
;     ...
;         if ((long)4 * F.G + F.bid >= (long)(MTOK / 256) * (DM / 256)) cvt_tables_drain(F, 3);
.LBB0_1410:
	s_or_b64 exec, exec, s[8:9]
	s_add_i32 s17, s17, 1
	s_cmp_eq_u32 s17, 1
	s_cselect_b64 s[8:9], -1, 0
